# attention inner loop: the eight V-fragment LDS reads of a key tile issued before the softmax arithmetic, one wait before the PV MFMAs
# baseline (speedup 1.0000x reference)
; __device__ __forceinline__ void attn_task(const Params& p, int l, int task, bool isctx, char* smem) {
;     ...
;     const int cur = base + hh * 16384;
;     f32x4 s[4][2];
; #pragma unroll
;     for (int i = 0; i < 4; ++i)
; #pragma unroll
;       for (int g = 0; g < 2; ++g) s[i][g] = f32x4{-Bsh, -Bsh, -Bsh, -Bsh};
;     __builtin_amdgcn_s_setprio(1);
; #pragma unroll
;     for (int i = 0; i < 4; ++i)
; #pragma unroll
;       for (int ks = 0; ks < 2; ++ks) {
;         const bf16x8 kf = *(const bf16x8*)(smem + cur + ((i * 2048 + inner) ^ (ks * 64)));
; #pragma unroll
;         for (int g = 0; g < 2; ++g) s[i][g] = __builtin_amdgcn_mfma_f32_16x16x32_bf16(kf, qB[g][ks], s[i][g], 0, 0, 0);
;       }
;     __builtin_amdgcn_s_setprio(0);
;     __builtin_amdgcn_sched_barrier(0);
;     bf16x8 pB[2][2];
; #pragma unroll
;     for (int g = 0; g < 2; ++g) {
;       float ps = 0.f;
; #pragma unroll
;       for (int i = 0; i < 4; ++i)
; #pragma unroll
;         for (int j = 0; j < 4; ++j) { const float pv = __builtin_amdgcn_exp2f(s[i][g][j]); s[i][g][j] = pv; ps += pv; }
;       lsum[g] += ps;
; #pragma unroll
;       for (int ii = 0; ii < 2; ++ii) {
;         union { u32x4 u; bf16x8 v; } cv;
;         cv.u.x = pack2(s[2 * ii][g][0], s[2 * ii][g][1]);
;         cv.u.y = pack2(s[2 * ii][g][2], s[2 * ii][g][3]);
;         cv.u.z = pack2(s[2 * ii + 1][g][0], s[2 * ii + 1][g][1]);
;         cv.u.w = pack2(s[2 * ii + 1][g][2], s[2 * ii + 1][g][3]);
;         pB[g][ii] = cv.v;
;       }
;     }
;     __builtin_amdgcn_sched_barrier(0);
;     __builtin_amdgcn_s_setprio(1);
; #pragma unroll
;     for (int mt = 0; mt < 4; ++mt)
; #pragma unroll
;       for (int ii = 0; ii < 2; ++ii) {
;         const bf16x8 vf = *(const bf16x8*)(smem + cur + 8192 + ((mt * 2048 + inner) ^ (ii * 64)));
; #pragma unroll
;         for (int g = 0; g < 2; ++g) O[mt][g] = __builtin_amdgcn_mfma_f32_16x16x32_bf16(vf, pB[g][ii], O[mt][g], 0, 0, 0);
;       }
;     __builtin_amdgcn_s_setprio(0);
.LBB0_119:
	s_or_b32 s48, s48, s47
	s_lshl_b32 s49, s48, 14
	s_mov_b32 s48, 1
	s_setprio 1
	v_or_b32_e32 v0, s49, v66
	ds_read_b128 v[68:71], v0
	ds_read_b128 v[72:75], v0 offset:2048
	v_or_b32_e32 v135, s49, v67
	ds_read_b128 v[80:83], v135
	ds_read_b128 v[84:87], v135 offset:2048
	s_waitcnt lgkmcnt(0)
	v_mfma_f32_16x16x32_bf16 v[76:79], v[68:71], v[26:29], v[50:53]
	v_mfma_f32_16x16x32_bf16 v[68:71], v[68:71], v[22:25], v[50:53]
	v_mfma_f32_16x16x32_bf16 v[76:79], v[80:83], v[18:21], v[76:79]
	v_mfma_f32_16x16x32_bf16 v[68:71], v[80:83], v[30:33], v[68:71]
	v_mfma_f32_16x16x32_bf16 v[80:83], v[72:75], v[26:29], v[50:53]
	v_mfma_f32_16x16x32_bf16 v[72:75], v[72:75], v[22:25], v[50:53]
	v_mfma_f32_16x16x32_bf16 v[80:83], v[84:87], v[18:21], v[80:83]
	v_mfma_f32_16x16x32_bf16 v[72:75], v[84:87], v[30:33], v[72:75]
	ds_read_b128 v[84:87], v0 offset:4096
	ds_read_b128 v[138:141], v0 offset:6144
	ds_read_b128 v[146:149], v135 offset:4096
	ds_read_b128 v[150:153], v135 offset:6144
	s_waitcnt lgkmcnt(0)
	v_mfma_f32_16x16x32_bf16 v[142:145], v[84:87], v[26:29], v[50:53]
	v_mfma_f32_16x16x32_bf16 v[84:87], v[84:87], v[22:25], v[50:53]
	v_mfma_f32_16x16x32_bf16 v[142:145], v[146:149], v[18:21], v[142:145]
	v_mfma_f32_16x16x32_bf16 v[84:87], v[146:149], v[30:33], v[84:87]
	v_mfma_f32_16x16x32_bf16 v[146:149], v[138:141], v[26:29], v[50:53]
	v_mfma_f32_16x16x32_bf16 v[138:141], v[138:141], v[22:25], v[50:53]
	v_mfma_f32_16x16x32_bf16 v[146:149], v[150:153], v[18:21], v[146:149]
	v_mfma_f32_16x16x32_bf16 v[138:141], v[150:153], v[30:33], v[138:141]
	s_setprio 0
	ds_read_b128 v[196:199], v0 offset:8192
	ds_read_b128 v[200:203], v135 offset:8192
	ds_read_b128 v[204:207], v0 offset:10240
	ds_read_b128 v[208:211], v135 offset:10240
	ds_read_b128 v[212:215], v0 offset:12288
	ds_read_b128 v[216:219], v135 offset:12288
	ds_read_b128 v[220:223], v0 offset:14336
	ds_read_b128 v[224:227], v135 offset:14336
	v_exp_f32_e32 v76, v76
	v_exp_f32_e32 v88, v77
	v_exp_f32_e32 v77, v68
	v_exp_f32_e32 v89, v69
	v_exp_f32_e32 v78, v78
	v_exp_f32_e32 v150, v79
	v_exp_f32_e32 v79, v70
	v_exp_f32_e32 v151, v71
	v_exp_f32_e32 v80, v80
	v_exp_f32_e32 v152, v81
	v_exp_f32_e32 v81, v72
	v_exp_f32_e32 v153, v73
	v_pk_add_f32 v[72:73], v[76:77], 0 op_sel_hi:[1,0]
	v_exp_f32_e32 v82, v82
	v_pk_add_f32 v[72:73], v[88:89], v[72:73]
	v_exp_f32_e32 v154, v83
	v_pk_add_f32 v[72:73], v[78:79], v[72:73]
	v_exp_f32_e32 v83, v74
	v_pk_add_f32 v[72:73], v[150:151], v[72:73]
	v_exp_f32_e32 v155, v75
	v_exp_f32_e32 v142, v142
	v_exp_f32_e32 v156, v143
	v_pk_add_f32 v[72:73], v[72:73], v[80:81]
	v_exp_f32_e32 v143, v84
	v_pk_add_f32 v[166:167], v[152:153], v[72:73]
	v_exp_f32_e32 v157, v85
	v_exp_f32_e32 v144, v144
	v_exp_f32_e32 v158, v145
	v_exp_f32_e32 v145, v86
	v_pk_add_f32 v[84:85], v[82:83], v[166:167]
	v_exp_f32_e32 v159, v87
	v_pk_add_f32 v[84:85], v[154:155], v[84:85]
	v_exp_f32_e32 v146, v146
	v_exp_f32_e32 v162, v147
	v_exp_f32_e32 v147, v138
	v_pk_add_f32 v[84:85], v[84:85], v[142:143]
	v_exp_f32_e32 v163, v139
	v_pk_add_f32 v[84:85], v[156:157], v[84:85]
	v_exp_f32_e32 v148, v148
	v_exp_f32_e32 v164, v149
	v_exp_f32_e32 v149, v140
	v_pk_add_f32 v[84:85], v[144:145], v[84:85]
	v_exp_f32_e32 v165, v141
	v_pk_add_f32 v[84:85], v[158:159], v[84:85]
	v_cvt_pk_bf16_f32 v68, v76, v88
	v_pk_add_f32 v[84:85], v[84:85], v[146:147]
	v_cvt_pk_bf16_f32 v69, v78, v150
	v_pk_add_f32 v[84:85], v[162:163], v[84:85]
	v_cvt_pk_bf16_f32 v70, v80, v152
	v_pk_add_f32 v[84:85], v[148:149], v[84:85]
	v_cvt_pk_bf16_f32 v71, v82, v154
	v_pk_add_f32 v[84:85], v[164:165], v[84:85]
	v_cvt_pk_bf16_f32 v72, v142, v156
	v_pk_add_f32 v[56:57], v[56:57], v[84:85]
	v_cvt_pk_bf16_f32 v73, v144, v158
	v_cvt_pk_bf16_f32 v74, v146, v162
	v_cvt_pk_bf16_f32 v75, v148, v164
	v_cvt_pk_bf16_f32 v76, v77, v89
	v_cvt_pk_bf16_f32 v77, v79, v151
	v_cvt_pk_bf16_f32 v78, v81, v153
	v_cvt_pk_bf16_f32 v79, v83, v155
	v_cvt_pk_bf16_f32 v80, v143, v157
	v_cvt_pk_bf16_f32 v81, v145, v159
	v_cvt_pk_bf16_f32 v82, v147, v163
	v_cvt_pk_bf16_f32 v83, v149, v165
	s_setprio 1
	s_waitcnt lgkmcnt(0)
	v_mfma_f32_16x16x32_bf16 v[42:45], v[196:199], v[68:71], v[42:45]
	v_mfma_f32_16x16x32_bf16 v[10:13], v[196:199], v[76:79], v[10:13]
	v_mfma_f32_16x16x32_bf16 v[42:45], v[200:203], v[72:75], v[42:45]
	v_mfma_f32_16x16x32_bf16 v[10:13], v[200:203], v[80:83], v[10:13]
	v_mfma_f32_16x16x32_bf16 v[38:41], v[204:207], v[68:71], v[38:41]
	v_mfma_f32_16x16x32_bf16 v[2:5], v[204:207], v[76:79], v[2:5]
	v_mfma_f32_16x16x32_bf16 v[38:41], v[208:211], v[72:75], v[38:41]
	v_mfma_f32_16x16x32_bf16 v[2:5], v[208:211], v[80:83], v[2:5]
	v_mfma_f32_16x16x32_bf16 v[34:37], v[212:215], v[68:71], v[34:37]
	v_mfma_f32_16x16x32_bf16 v[6:9], v[212:215], v[76:79], v[6:9]
	v_mfma_f32_16x16x32_bf16 v[34:37], v[216:219], v[72:75], v[34:37]
	v_mfma_f32_16x16x32_bf16 v[6:9], v[216:219], v[80:83], v[6:9]
	v_mfma_f32_16x16x32_bf16 v[46:49], v[220:223], v[68:71], v[46:49]
	v_mfma_f32_16x16x32_bf16 v[14:17], v[220:223], v[76:79], v[14:17]
	v_mfma_f32_16x16x32_bf16 v[46:49], v[224:227], v[72:75], v[46:49]
	v_mfma_f32_16x16x32_bf16 v[14:17], v[224:227], v[80:83], v[14:17]
	s_setprio 0
	s_andn2_b64 vcc, exec, s[42:43]
	s_mov_b64 s[42:43], 0
	s_cbranch_vccz .LBB0_119
	s_waitcnt vmcnt(0)
	s_and_b64 vcc, exec, s[40:41]
	s_barrier
	s_cbranch_vccnz .LBB0_122
	s_mov_b32 s42, s46
	s_branch .LBB0_116
